# XCD-local barrier: the last arriver (its atomic's return value completes the count) leaves without polling; the others poll without s_sleep
# baseline (speedup 1.0000x reference)
; __device__ __forceinline__ unsigned xb_ld(unsigned* p)              { return __hip_atomic_load(p, __ATOMIC_RELAXED, __HIP_MEMORY_SCOPE_AGENT); }
; __device__ __forceinline__ unsigned xb_add(unsigned* p, unsigned v) { return __hip_atomic_fetch_add(p, v, __ATOMIC_RELAXED, __HIP_MEMORY_SCOPE_AGENT); }
; #define XB_SPIN(cond, bar) do { unsigned _sp = 0; while (cond) { __builtin_amdgcn_s_sleep(1); \
;     if ((++_sp & 255u) == 0u) { if (xb_ld(&(bar)[XB_TMO])) break; if (_sp > XB_SPIN_CAP) { atomicAdd(&(bar)[XB_TMO], 1u); break; } } } } while (0)
; __device__ __forceinline__ void xcd_barrier(const XcdBarrier& b) {
;     ...
;         const unsigned old = xb_add(&bar[XB_XSUB(bx)], 1u);
;         const unsigned gen = old / nloc;
;         if (old + 1u == (gen + 1u) * nloc) {
;             __builtin_amdgcn_fence(__ATOMIC_RELEASE, "agent");
;             asm volatile("s_waitcnt vmcnt(0)" ::: "memory");
;             const unsigned og = xb_add(&bar[XB_TOP], 1u);
;             const unsigned tg = og / nx;
;             if (og + 1u == (tg + 1u) * nx) xb_add(&bar[XB_TOPGEN], 1u);
;             else XB_SPIN(xb_ld(&bar[XB_TOPGEN]) == tg, bar);
;             __builtin_amdgcn_fence(__ATOMIC_ACQUIRE, "agent");
;             xb_add(&bar[XB_XGEN(bx)], 1u);
;             asm volatile("s_waitcnt vmcnt(0)" ::: "memory");
;         } else {
;             XB_SPIN(xb_ld(&bar[XB_XGEN(bx)]) == gen, bar);
.Lwc_pskip_2:
	s_cmp_eq_u32 s99, 0
	s_cbranch_scc1 .Lxb_full_1
	v_readlane_b32 s2, v254, 2
	v_mov_b32_e32 v1, 1
	s_lshl_b32 s2, s2, 8
	s_mov_b32 s98, 0
	v_mov_b32_e32 v0, s2
	buffer_inv sc1
	global_atomic_add v1, v0, v1, s[82:83] offset:1152 sc0
	s_waitcnt vmcnt(0)
	v_add_u32_e32 v2, 1, v1
	v_lshrrev_b32_e32 v1, 5, v1
	v_add_u32_e32 v1, 1, v1
	v_lshlrev_b32_e32 v1, 5, v1
	v_cmp_eq_u32_e32 vcc, v2, v1
	s_cbranch_vccnz .Lxb_done_1
.Lxb_spin_1:
	global_load_dword v2, v0, s[82:83] offset:1152 sc1
	s_add_u32 s98, s98, 1
	s_waitcnt vmcnt(0)
	v_cmp_lt_u32_e32 vcc, v2, v1
	s_cbranch_vccz .Lxb_done_1
	s_cmp_lt_u32 s98, 0x100000
	s_cbranch_scc0 .Lxb_done_1
	s_branch .Lxb_spin_1

; __device__ __forceinline__ unsigned xb_ld(unsigned* p)              { return __hip_atomic_load(p, __ATOMIC_RELAXED, __HIP_MEMORY_SCOPE_AGENT); }
; __device__ __forceinline__ unsigned xb_add(unsigned* p, unsigned v) { return __hip_atomic_fetch_add(p, v, __ATOMIC_RELAXED, __HIP_MEMORY_SCOPE_AGENT); }
; #define XB_SPIN(cond, bar) do { unsigned _sp = 0; while (cond) { __builtin_amdgcn_s_sleep(1); \
;     if ((++_sp & 255u) == 0u) { if (xb_ld(&(bar)[XB_TMO])) break; if (_sp > XB_SPIN_CAP) { atomicAdd(&(bar)[XB_TMO], 1u); break; } } } } while (0)
; __device__ __forceinline__ void xcd_barrier(const XcdBarrier& b) {
;     ...
;         const unsigned old = xb_add(&bar[XB_XSUB(bx)], 1u);
;         const unsigned gen = old / nloc;
;         if (old + 1u == (gen + 1u) * nloc) {
;             __builtin_amdgcn_fence(__ATOMIC_RELEASE, "agent");
;             asm volatile("s_waitcnt vmcnt(0)" ::: "memory");
;             const unsigned og = xb_add(&bar[XB_TOP], 1u);
;             const unsigned tg = og / nx;
;             if (og + 1u == (tg + 1u) * nx) xb_add(&bar[XB_TOPGEN], 1u);
;             else XB_SPIN(xb_ld(&bar[XB_TOPGEN]) == tg, bar);
;             __builtin_amdgcn_fence(__ATOMIC_ACQUIRE, "agent");
;             xb_add(&bar[XB_XGEN(bx)], 1u);
;             asm volatile("s_waitcnt vmcnt(0)" ::: "memory");
;         } else {
;             XB_SPIN(xb_ld(&bar[XB_XGEN(bx)]) == gen, bar);
.Lwc_iskip_a4:
	s_and_saveexec_b64 s[0:1], s[66:67]
	s_cbranch_execz .LBB0_101
	v_mov_b32_e32 v61, 0
	global_load_dword v60, v61, s[82:83] offset:256 sc1
	s_cmp_eq_u32 s99, 0
	s_cbranch_scc1 .Lxb_full_3
	v_readlane_b32 s2, v254, 2
	v_mov_b32_e32 v1, 1
	s_lshl_b32 s2, s2, 8
	s_mov_b32 s98, 0
	v_mov_b32_e32 v0, s2
	buffer_inv sc1
	global_atomic_add v1, v0, v1, s[82:83] offset:1152 sc0
	s_waitcnt vmcnt(0)
	v_add_u32_e32 v2, 1, v1
	v_lshrrev_b32_e32 v1, 5, v1
	v_add_u32_e32 v1, 1, v1
	v_lshlrev_b32_e32 v1, 5, v1
	v_cmp_eq_u32_e32 vcc, v2, v1
	s_cbranch_vccnz .Lxb_done_3
